# phase 10: static s_setprio 1 for waves 4-7 (one wave of every SIMD pair) so the two waves stop running the gather loops in lockstep
# speedup vs baseline: 1.0005x; 1.0005x over previous
.LBB0_2035:
	s_cmp_lt_i32 s94, 11
	s_cselect_b64 s[2:3], -1, 0
	s_and_b64 s[0:1], s[2:3], s[0:1]
	s_andn2_b64 vcc, exec, s[0:1]
	s_cbranch_vccnz .LBB0_2059
	v_readfirstlane_b32 s98, v187
	s_cmp_lt_u32 s98, 4
	s_cbranch_scc1 .Lp10_noprio
	s_setprio 1
.Lp10_noprio:
	s_load_dword s49, s[68:69], 0xe0
	s_movk_i32 s33, 0x4400
	s_waitcnt lgkmcnt(0)
	v_mul_lo_u32 v1, s49, v187
	s_waitcnt vmcnt(0)
	v_add_u32_e32 v123, s70, v1
	v_cmp_gt_i32_e32 vcc, s33, v123
	s_and_saveexec_b64 s[0:1], vcc
	s_cbranch_execz .LBB0_2059
	v_lshlrev_b32_e32 v2, 4, v0
	v_and_b32_e32 v3, 0x1c00, v2
	v_lshlrev_b32_e32 v2, 2, v0
	v_and_b32_e32 v105, 7, v0
	v_and_b32_e32 v104, 0xe0, v2
	v_or_b32_e32 v2, 24, v105
	v_cmp_gt_u32_e32 vcc, 29, v2
	v_add_u32_e32 v4, -5, v105
	v_or_b32_e32 v5, 16, v104
	v_cndmask_b32_e64 v6, 3, 2, vcc
	v_cndmask_b32_e32 v4, v4, v105, vcc
	v_or_b32_e32 v2, v6, v104
	v_mul_i32_i24_e32 v6, -16, v6
	v_add_u32_e32 v108, v4, v5
	v_sub_u32_e32 v4, v6, v4
	v_add_u32_e32 v110, 0xff, v4
	v_or_b32_e32 v4, 40, v105
	v_add_u32_e32 v6, 6, v105
	v_cmp_gt_u32_e32 vcc, 42, v4
	s_lshl_b32 s48, s49, 3
	s_add_u32 s28, s92, 0x25635000
	v_cndmask_b32_e64 v8, v6, 7, vcc
	v_or_b32_e32 v6, v8, v104
	v_lshlrev_b32_e32 v13, 4, v8
	v_or_b32_e32 v8, 48, v105
	s_addc_u32 s29, s93, 0
	v_mov_b32_e32 v107, 0
	v_cmp_gt_u32_e64 s[0:1], 50, v8
	v_mov_b32_e32 v8, 0xe0
	v_lshlrev_b32_e32 v106, 4, v250
	s_add_u32 s30, s92, 0x26735000
	v_lshl_add_u32 v125, v105, 4, v8
	v_lshl_add_u64 v[8:9], s[92:93], 0, v[106:107]
	s_mov_b64 s[16:17], 0xdf05000
	s_addc_u32 s31, s93, 0
	v_lshl_add_u64 v[114:115], v[8:9], 0, s[16:17]
	s_add_i32 s16, 0, 0x14000
	s_movk_i32 s18, 0x2400
	v_mov_b32_e32 v10, s16
	v_mad_u32_u24 v15, v187, s18, v10
	v_lshrrev_b32_e32 v10, 2, v250
	v_mul_u32_u24_e32 v19, 0x50, v10
	s_mov_b64 s[16:17], 0x5204000
	v_and_b32_e32 v10, 32, v0
	v_or_b32_e32 v7, 32, v105
	v_lshl_add_u64 v[116:117], v[8:9], 0, s[16:17]
	v_cmp_eq_u32_e64 s[16:17], 0, v10
	v_and_b32_e32 v10, 16, v0
	v_cndmask_b32_e32 v4, 0, v105, vcc
	v_mad_u32_u24 v157, v187, s18, 0
	v_cmp_eq_u32_e64 s[18:19], 0, v10
	v_and_b32_e32 v10, 8, v0
	s_mov_b64 s[26:27], 0x9204000
	v_cmp_gt_u32_e32 vcc, 38, v7
	v_cmp_eq_u32_e64 s[20:21], 0, v10
	v_and_b32_e32 v10, 4, v0
	v_lshl_add_u64 v[118:119], v[8:9], 0, s[26:27]
	v_subrev_co_u32_e64 v24, s[26:27], 1, v105
	v_cndmask_b32_e64 v27, -6, -4, vcc
	v_mul_u32_u24_e32 v1, 0x2400, v187
	v_cmp_eq_u32_e64 s[22:23], 0, v10
	v_and_b32_e32 v10, 3, v0
	v_cndmask_b32_e64 v24, v24, 3, s[26:27]
	v_cndmask_b32_e64 v26, 4, 3, s[26:27]
	v_add_u32_e32 v27, v105, v27
	v_cndmask_b32_e64 v28, 6, 5, vcc
	v_cmp_gt_u32_e32 vcc, 36, v7
	v_and_b32_e32 v0, 60, v0
	v_and_b32_e32 v12, 48, v106
	s_add_u32 s34, s92, 0x27835000
	v_cndmask_b32_e32 v7, v27, v24, vcc
	v_cndmask_b32_e32 v26, v28, v26, vcc
	v_or_b32_e32 v1, v1, v0
	v_or_b32_e32 v0, v3, v0
	v_lshlrev_b32_e32 v112, 3, v250
	v_mov_b32_e32 v113, v107
	v_add_u32_e32 v17, v15, v12
	s_addc_u32 s35, s93, 0
	v_cmp_eq_u32_e64 s[24:25], 0, v10
	v_lshlrev_b32_e32 v8, 2, v250
	v_lshrrev_b32_e32 v10, 3, v250
	v_and_b32_e32 v12, 0x70, v106
	v_add_u32_e32 v120, v7, v5
	v_mul_i32_i24_e32 v5, -16, v26
	v_add_u32_e32 v161, 0, v0
	v_xor_b32_e32 v11, 0xff, v4
	v_mul_u32_u24_e32 v21, 0x50, v250
	s_add_u32 s36, s92, 0x27935000
	v_mul_u32_u24_e32 v9, 0x90, v250
	v_add_u32_e32 v23, v15, v12
	v_mul_u32_u24_e32 v25, 0x90, v10
	v_or_b32_e32 v10, 0x100, v8
	v_or_b32_e32 v12, 0x200, v8
	v_or_b32_e32 v14, 0x300, v8
	v_or_b32_e32 v16, 0x400, v8
	v_or_b32_e32 v18, 0x500, v8
	v_or_b32_e32 v20, 0x600, v8
	v_or_b32_e32 v22, 0x700, v8
	v_or_b32_e32 v24, v26, v104
	v_sub_u32_e32 v5, v5, v7
	v_lshl_add_u64 v[26:27], s[92:93], 0, v[112:113]
	s_mov_b64 s[38:39], 0x12305000
	v_add_u32_e32 v1, 0, v1
	v_mbcnt_lo_u32_b32 v0, -1, 0
	s_mulk_i32 s49, 0x48
	v_mov_b32_e32 v109, v107
	s_movk_i32 s50, 0xff
	v_cmp_eq_u32_e64 s[2:3], 1, v105
	v_cmp_eq_u32_e64 s[4:5], 2, v105
	v_cmp_eq_u32_e64 s[6:7], 3, v105
	v_cmp_eq_u32_e64 s[8:9], 4, v105
	v_cmp_eq_u32_e64 s[10:11], 5, v105
	v_cmp_eq_u32_e64 s[12:13], 6, v105
	v_cmp_eq_u32_e64 s[14:15], 7, v105
	s_addc_u32 s37, s93, 0
	v_add3_u32 v159, 0, v3, v112
	v_mov_b32_e32 v121, v107
	v_sub_u32_e32 v122, v11, v13
	v_add_u32_e32 v111, 0xff, v5
	v_mov_b32_e32 v124, v105
	v_lshl_add_u64 v[126:127], v[26:27], 0, s[38:39]
	v_add_u32_e32 v113, 0x2000, v1
	v_add_u32_e32 v162, 0x2000, v157
	s_mov_b64 s[38:39], 0
	v_lshlrev_b32_e32 v128, 2, v2
	v_lshlrev_b32_e32 v130, 2, v24
	v_lshlrev_b32_e32 v132, 2, v6
	v_lshlrev_b32_e32 v134, 2, v4
	s_movk_i32 s51, 0xf7
	v_add_u32_e32 v163, v17, v19
	v_add_u32_e32 v164, v15, v21
	s_mov_b32 s52, 0x378e98ab
	s_mov_b32 s53, 0x3b7cd369
	s_mov_b32 s54, 0xbcc618b2
	s_mov_b32 s55, 0x3dda74e4
	s_mov_b32 s56, 0x3f228afd
	s_mov_b32 s57, 0x3e03c728
	s_mov_b32 s58, 0xbfb8aa3b
	s_mov_b32 s59, 0x42ce8ed0
	s_mov_b32 s60, 0xc2b17218
	v_mov_b32_e32 v165, 0x3ba10414
	v_add_u32_e32 v166, v15, v9
	s_movk_i32 s61, 0x4000
	s_mov_b32 s62, 0xc000
	s_mov_b64 s[40:41], 0xd30f000
	v_add_u32_e32 v167, v23, v25
	v_lshlrev_b32_e32 v136, 2, v8
	v_lshlrev_b32_e32 v138, 2, v10
	v_lshlrev_b32_e32 v140, 2, v12
	v_lshlrev_b32_e32 v142, 2, v14
	v_lshlrev_b32_e32 v144, 2, v16
	v_lshlrev_b32_e32 v146, 2, v18
	v_lshlrev_b32_e32 v148, 2, v20
	v_lshlrev_b32_e32 v150, 2, v22
	s_movk_i32 s63, 0x43ff
	v_mbcnt_hi_u32_b32 v168, -1, v0
	v_mov_b32_e32 v169, 0xb9c68948
	v_mov_b32_e32 v170, 0x7f800000
	v_and_b32_e32 v248, 15, v168
	v_and_b32_e32 v249, 48, v168
	v_add_u32_e32 v199, 0, v248
	v_and_b32_e32 v199, 15, v199
	v_or_b32_e32 v199, v199, v249
	v_lshlrev_b32_e32 v200, 4, v199
	v_add_u32_e32 v200, 0x5204000, v200
	v_add_u32_e32 v199, 1, v248
	v_and_b32_e32 v199, 15, v199
	v_or_b32_e32 v199, v199, v249
	v_lshlrev_b32_e32 v201, 4, v199
	v_add_u32_e32 v201, 0x5204000, v201
	v_add_u32_e32 v199, 2, v248
	v_and_b32_e32 v199, 15, v199
	v_or_b32_e32 v199, v199, v249
	v_lshlrev_b32_e32 v202, 4, v199
	v_add_u32_e32 v202, 0x5204000, v202
	v_add_u32_e32 v199, 3, v248
	v_and_b32_e32 v199, 15, v199
	v_or_b32_e32 v199, v199, v249
	v_lshlrev_b32_e32 v203, 4, v199
	v_add_u32_e32 v203, 0x5204000, v203
	v_add_u32_e32 v199, 4, v248
	v_and_b32_e32 v199, 15, v199
	v_or_b32_e32 v199, v199, v249
	v_lshlrev_b32_e32 v204, 4, v199
	v_add_u32_e32 v204, 0x5204000, v204
	v_add_u32_e32 v199, 5, v248
	v_and_b32_e32 v199, 15, v199
	v_or_b32_e32 v199, v199, v249
	v_lshlrev_b32_e32 v205, 4, v199
	v_add_u32_e32 v205, 0x5204000, v205
	v_add_u32_e32 v199, 6, v248
	v_and_b32_e32 v199, 15, v199
	v_or_b32_e32 v199, v199, v249
	v_lshlrev_b32_e32 v206, 4, v199
	v_add_u32_e32 v206, 0x5204000, v206
	v_add_u32_e32 v199, 7, v248
	v_and_b32_e32 v199, 15, v199
	v_or_b32_e32 v199, v199, v249
	v_lshlrev_b32_e32 v207, 4, v199
	v_add_u32_e32 v207, 0x5204000, v207
	v_add_u32_e32 v199, 8, v248
	v_and_b32_e32 v199, 15, v199
	v_or_b32_e32 v199, v199, v249
	v_lshlrev_b32_e32 v208, 4, v199
	v_add_u32_e32 v208, 0x5204000, v208
	v_add_u32_e32 v199, 9, v248
	v_and_b32_e32 v199, 15, v199
	v_or_b32_e32 v199, v199, v249
	v_lshlrev_b32_e32 v209, 4, v199
	v_add_u32_e32 v209, 0x5204000, v209
	v_add_u32_e32 v199, 10, v248
	v_and_b32_e32 v199, 15, v199
	v_or_b32_e32 v199, v199, v249
	v_lshlrev_b32_e32 v210, 4, v199
	v_add_u32_e32 v210, 0x5204000, v210
	v_add_u32_e32 v199, 11, v248
	v_and_b32_e32 v199, 15, v199
	v_or_b32_e32 v199, v199, v249
	v_lshlrev_b32_e32 v211, 4, v199
	v_add_u32_e32 v211, 0x5204000, v211
	v_add_u32_e32 v199, 12, v248
	v_and_b32_e32 v199, 15, v199
	v_or_b32_e32 v199, v199, v249
	v_lshlrev_b32_e32 v212, 4, v199
	v_add_u32_e32 v212, 0x5204000, v212
	v_add_u32_e32 v199, 13, v248
	v_and_b32_e32 v199, 15, v199
	v_or_b32_e32 v199, v199, v249
	v_lshlrev_b32_e32 v213, 4, v199
	v_add_u32_e32 v213, 0x5204000, v213
	v_add_u32_e32 v199, 14, v248
	v_and_b32_e32 v199, 15, v199
	v_or_b32_e32 v199, v199, v249
	v_lshlrev_b32_e32 v214, 4, v199
	v_add_u32_e32 v214, 0x5204000, v214
	v_add_u32_e32 v199, 15, v248
	v_and_b32_e32 v199, 15, v199
	v_or_b32_e32 v199, v199, v249
	v_lshlrev_b32_e32 v215, 4, v199
	v_add_u32_e32 v215, 0x5204000, v215
	v_lshlrev_b32_e32 v216, 4, v168
	v_add_u32_e32 v216, 0x9204000, v216
	v_lshrrev_b32_e32 v199, 2, v249
	v_add3_u32 v217, v248, v199, 0
	v_and_b32_e32 v217, 15, v217
	v_or_b32_e32 v217, v217, v249
	v_lshlrev_b32_e32 v217, 2, v217
	v_add3_u32 v218, v248, v199, 1
	v_and_b32_e32 v218, 15, v218
	v_or_b32_e32 v218, v218, v249
	v_lshlrev_b32_e32 v218, 2, v218
	v_add3_u32 v219, v248, v199, 2
	v_and_b32_e32 v219, 15, v219
	v_or_b32_e32 v219, v219, v249
	v_lshlrev_b32_e32 v219, 2, v219
	v_add3_u32 v220, v248, v199, 3
	v_and_b32_e32 v220, 15, v220
	v_or_b32_e32 v220, v220, v249
	v_lshlrev_b32_e32 v220, 2, v220
	v_and_b32_e32 v221, 60, v168
	v_sub_u32_e32 v199, v248, v199
	v_and_b32_e32 v199, 15, v199
	v_cmp_eq_u32_e32 vcc, 0, v199
	s_nop 1
	v_cndmask_b32_e64 v222, 0, 1.0, vcc
	v_cmp_eq_u32_e32 vcc, 1, v199
	s_nop 1
	v_cndmask_b32_e64 v223, 0, 1.0, vcc
	v_cmp_eq_u32_e32 vcc, 2, v199
	s_nop 1
	v_cndmask_b32_e64 v224, 0, 1.0, vcc
	v_cmp_eq_u32_e32 vcc, 3, v199
	s_nop 1
	v_cndmask_b32_e64 v225, 0, 1.0, vcc
	v_cmp_eq_u32_e32 vcc, 4, v199
	s_nop 1
	v_cndmask_b32_e64 v226, 0, 1.0, vcc
	v_cmp_eq_u32_e32 vcc, 5, v199
	s_nop 1
	v_cndmask_b32_e64 v227, 0, 1.0, vcc
	v_cmp_eq_u32_e32 vcc, 6, v199
	s_nop 1
	v_cndmask_b32_e64 v228, 0, 1.0, vcc
	v_cmp_eq_u32_e32 vcc, 7, v199
	s_nop 1
	v_cndmask_b32_e64 v229, 0, 1.0, vcc
	v_cmp_eq_u32_e32 vcc, 8, v199
	s_nop 1
	v_cndmask_b32_e64 v230, 0, 1.0, vcc
	v_cmp_eq_u32_e32 vcc, 9, v199
	s_nop 1
	v_cndmask_b32_e64 v231, 0, 1.0, vcc
	v_cmp_eq_u32_e32 vcc, 10, v199
	s_nop 1
	v_cndmask_b32_e64 v232, 0, 1.0, vcc
	v_cmp_eq_u32_e32 vcc, 11, v199
	s_nop 1
	v_cndmask_b32_e64 v233, 0, 1.0, vcc
	v_cmp_eq_u32_e32 vcc, 12, v199
	s_nop 1
	v_cndmask_b32_e64 v234, 0, 1.0, vcc
	v_cmp_eq_u32_e32 vcc, 13, v199
	s_nop 1
	v_cndmask_b32_e64 v235, 0, 1.0, vcc
	v_cmp_eq_u32_e32 vcc, 14, v199
	s_nop 1
	v_cndmask_b32_e64 v236, 0, 1.0, vcc
	v_cmp_eq_u32_e32 vcc, 15, v199
	s_nop 1
	v_cndmask_b32_e64 v237, 0, 1.0, vcc
	s_branch .LBB0_2039
